# v38 + LDS swizzle + pipelined GEMM K-loops with waves 4-7 staggered by half a K-step
# baseline (speedup 1.0000x reference)
; template <int MODE, bool SWAP, int MT>
; DI void gemm_tile(const int wv_, const Params& p, const u16* __restrict__ A, const u16* __restrict__ Bt, int brow, int bcol, char* smem, const float* gnext) {
;     ...
;   const int tid = tid_, wid = tid >> 6, lane = tid & 63, wr = wid >> 1, wc = wid & 1, fr = lane & 15, fq = lane >> 4;
;   f32x4 acc[MT][4];
; #pragma unroll
;   for (int m = 0; m < MT; ++m)
; #pragma unroll
;     for (int n = 0; n < 4; ++n) acc[m][n] = f32x4{0.f, 0.f, 0.f, 0.f};
;   const int ra = tid >> 2, cb = (tid & 3) * 8;
;   const u16* ga0 = A + (size_t)(brow + ra) * 1024 + cb;
;   const u16* ga1 = A + (size_t)(brow + 128 + ra) * 1024 + cb;
;   const u16* gb0 = Bt + (size_t)(bcol + ra) * 1024 + cb;
;   auto stage = [&](int t, int buf) {
;     char* sA = smem + buf * 24576; char* sB = sA + 16384;
;     if (MT >= 2 || tid < 256) __builtin_amdgcn_global_load_lds((const unsigned*)(ga0 + t * 32), (unsigned*)(sA + tid * 16), 16, 0, 0);
;     if (MT == 4) __builtin_amdgcn_global_load_lds((const unsigned*)(ga1 + t * 32), (unsigned*)(sA + 8192 + tid * 16), 16, 0, 0);
;     __builtin_amdgcn_global_load_lds((const unsigned*)(gb0 + t * 32), (unsigned*)(sB + tid * 16), 16, 0, 0);
;   };
;   stage(0, 0);
;   for (int t = 0; t < 32; ++t) {
;     asm volatile("s_waitcnt vmcnt(0)" ::: "memory");
;     __syncthreads();
;     if (t + 1 < 32) stage(t + 1, (t + 1) & 1);
;     const char* sA = smem + (t & 1) * 24576; const char* sB = sA + 16384;
;     bf16x8 Af[MT], Bf[4];
; #pragma unroll
;     for (int n = 0; n < 4; ++n) Bf[n] = *(const bf16x8*)(sB + (wc * 64 + n * 16 + fr) * 64 + fq * 16);
;     constexpr int MH = MT >= 2 ? MT / 2 : 1;
; #pragma unroll
;     for (int m = 0; m < MH; ++m) Af[m] = *(const bf16x8*)(sA + (wr * (16 * MT) + m * 16 + fr) * 64 + fq * 16);
.LBB0_84:
	s_mul_hi_i32 s0, s14, 0x92492493
	s_add_i32 s0, s0, s14
	s_lshr_b32 s1, s0, 31
	s_ashr_i32 s0, s0, 4
	s_add_i32 s19, s0, s1
	s_mul_i32 s0, s19, 0xffffffe4
	s_add_i32 s0, s0, s14
	s_and_b32 s1, s0, -4
	s_lshl_b32 s18, s19, 8
	s_lshl_b32 s15, s0, 7
	s_cmp_lg_u32 s1, 20
	s_mov_b64 s[0:1], -1
	s_mulk_i32 s19, 0xe00
	s_cbranch_scc0 .LBB0_88
	s_mov_b32 s1, 0
	v_readlane_b32 s20, v127, 0
	v_mbcnt_lo_u32_b32 v0, -1, s1
	v_mbcnt_hi_u32_b32 v0, -1, v0
	v_add_u32_e32 v12, s33, v0
	s_mov_b32 s1, s16
	v_ashrrev_i32_e32 v13, 2, v12
	v_add_u32_e32 v0, s18, v13
	s_mov_b32 s1, s17
	v_ashrrev_i32_e32 v1, 31, v0
	v_lshlrev_b64 v[4:5], 11, v[0:1]
	v_readlane_b32 s21, v127, 1
	v_lshlrev_b32_e32 v76, 4, v12
	v_lshrrev_b32_e32 v2, 8, v76
	v_sub_u32_e32 v2, 0, v2
	v_lshlrev_b32_e32 v2, 4, v2
	v_xor_b32_e32 v2, v2, v76
	v_and_b32_e32 v2, 48, v2
	v_lshl_add_u64 v[6:7], s[20:21], 0, v[4:5]
	v_add_u32_e32 v0, 0x80, v0
	v_readfirstlane_b32 s1, v76
	v_lshl_add_u64 v[6:7], v[6:7], 0, v[2:3]
	v_ashrrev_i32_e32 v1, 31, v0
	s_mov_b32 m0, s1
	v_lshlrev_b64 v[8:9], 11, v[0:1]
	global_load_lds_dwordx4 v[6:7], off
	v_add_u32_e32 v6, 0x2000, v76
	v_lshl_add_u64 v[0:1], s[20:21], 0, v[8:9]
	v_add_u32_e32 v10, s15, v13
	v_readfirstlane_b32 s1, v6
	v_lshl_add_u64 v[0:1], v[0:1], 0, v[2:3]
	v_ashrrev_i32_e32 v11, 31, v10
	s_mov_b32 m0, s1
	v_lshlrev_b64 v[10:11], 11, v[10:11]
	global_load_lds_dwordx4 v[0:1], off
	v_add_u32_e32 v0, 0x4000, v76
	v_lshl_add_u64 v[10:11], s[2:3], 0, v[10:11]
	v_readfirstlane_b32 s1, v0
	v_lshl_add_u64 v[10:11], v[10:11], 0, v[2:3]
	s_mov_b32 m0, s1
	v_and_b32_e32 v74, 15, v12
	global_load_lds_dwordx4 v[10:11], off
	v_readlane_b32 s20, v127, 22
	v_bfe_u32 v72, v12, 6, 1
	v_ashrrev_i32_e32 v73, 7, v12
	v_lshlrev_b32_e32 v0, 6, v74
	v_or_b32_e32 v4, v4, v2
	v_readlane_b32 s21, v127, 23
	v_lshl_or_b32 v78, v72, 12, v0
	v_lshl_or_b32 v79, v73, 12, v0
	v_lshl_add_u64 v[0:1], s[20:21], 0, v[4:5]
	v_add_u32_e32 v4, s12, v13
	v_subrev_u32_e32 v4, s19, v4
	v_ashrrev_i32_e32 v5, 31, v4
	v_lshlrev_b64 v[4:5], 11, v[4:5]
	v_or_b32_e32 v4, v4, v2
	v_bfe_u32 v75, v12, 4, 2
	v_or_b32_e32 v8, v8, v2
	v_lshl_add_u64 v[70:71], s[4:5], 0, v[4:5]
	v_mov_b32_e32 v4, 0
	s_mov_b32 s0, 0
	v_lshrrev_b32_e32 v77, 2, v74
	v_sub_u32_e32 v77, 0, v77
	v_xor_b32_e32 v77, v77, v75
	v_and_b32_e32 v77, 3, v77
	v_lshlrev_b32_e32 v77, 4, v77
	v_lshl_add_u64 v[68:69], s[20:21], 0, v[8:9]
	v_mov_b32_e32 v5, v4
	v_mov_b32_e32 v6, v4
	v_mov_b32_e32 v7, v4
	v_mov_b32_e32 v8, v4
	v_mov_b32_e32 v9, v4
	v_mov_b32_e32 v10, v4
	v_mov_b32_e32 v11, v4
	v_mov_b32_e32 v12, v4
	v_mov_b32_e32 v13, v4
	v_mov_b32_e32 v14, v4
	v_mov_b32_e32 v15, v4
	v_mov_b32_e32 v16, v4
	v_mov_b32_e32 v17, v4
	v_mov_b32_e32 v18, v4
	v_mov_b32_e32 v19, v4
	v_mov_b32_e32 v20, v4
	v_mov_b32_e32 v21, v4
	v_mov_b32_e32 v22, v4
	v_mov_b32_e32 v23, v4
	v_mov_b32_e32 v24, v4
	v_mov_b32_e32 v25, v4
	v_mov_b32_e32 v26, v4
	v_mov_b32_e32 v27, v4
	v_mov_b32_e32 v28, v4
	v_mov_b32_e32 v29, v4
	v_mov_b32_e32 v30, v4
	v_mov_b32_e32 v31, v4
	v_mov_b32_e32 v32, v4
	v_mov_b32_e32 v33, v4
	v_mov_b32_e32 v34, v4
	v_mov_b32_e32 v35, v4
	v_mov_b32_e32 v44, v4
	v_mov_b32_e32 v45, v4
	v_mov_b32_e32 v46, v4
	v_mov_b32_e32 v47, v4
	v_mov_b32_e32 v36, v4
	v_mov_b32_e32 v37, v4
	v_mov_b32_e32 v38, v4
	v_mov_b32_e32 v39, v4
	v_mov_b32_e32 v40, v4
	v_mov_b32_e32 v41, v4
	v_mov_b32_e32 v42, v4
	v_mov_b32_e32 v43, v4
	v_mov_b32_e32 v48, v4
	v_mov_b32_e32 v49, v4
	v_mov_b32_e32 v50, v4
	v_mov_b32_e32 v51, v4
	v_mov_b32_e32 v52, v4
	v_mov_b32_e32 v53, v4
	v_mov_b32_e32 v54, v4
	v_mov_b32_e32 v55, v4
	v_mov_b32_e32 v56, v4
	v_mov_b32_e32 v57, v4
	v_mov_b32_e32 v58, v4
	v_mov_b32_e32 v59, v4
	v_mov_b32_e32 v60, v4
	v_mov_b32_e32 v61, v4
	v_mov_b32_e32 v62, v4
	v_mov_b32_e32 v63, v4
	v_mov_b32_e32 v64, v4
	v_mov_b32_e32 v65, v4
	v_mov_b32_e32 v66, v4
	v_mov_b32_e32 v67, v4
	v_readlane_b32 s22, v127, 2
	v_readlane_b32 s23, v127, 3
	v_readfirstlane_b32 s98, v76
	s_movk_i32 s99, 0x6000
	s_add_i32 s101, s98, s99
	s_mov_b32 m0, s101
	s_add_i32 s101, s101, 0x2000
	global_load_lds_dwordx4 v[0:1], off
	s_mov_b32 m0, s101
	s_add_i32 s101, s101, 0x2000
	global_load_lds_dwordx4 v[68:69], off
	s_mov_b32 m0, s101
	s_add_i32 s99, s99, 0x6000
	global_load_lds_dwordx4 v[70:71], off
	s_cmp_eq_u32 s99, 0x12000
	s_cselect_b32 s99, 0, s99
	v_lshl_add_u64 v[0:1], v[0:1], 0, 64
	v_lshl_add_u64 v[68:69], v[68:69], 0, 64
	v_lshl_add_u64 v[70:71], v[70:71], 0, 64
	s_add_i32 s101, s98, s99
	s_mov_b32 m0, s101
	s_add_i32 s101, s101, 0x2000
	global_load_lds_dwordx4 v[0:1], off
	s_mov_b32 m0, s101
	s_add_i32 s101, s101, 0x2000
	global_load_lds_dwordx4 v[68:69], off
	s_mov_b32 m0, s101
	s_add_i32 s99, s99, 0x6000
	global_load_lds_dwordx4 v[70:71], off
	s_cmp_eq_u32 s99, 0x12000
	s_cselect_b32 s99, 0, s99
	v_lshl_add_u64 v[0:1], v[0:1], 0, 64
	v_lshl_add_u64 v[68:69], v[68:69], 0, 64
	v_lshl_add_u64 v[70:71], v[70:71], 0, 64
	s_mov_b32 s100, 0
	s_waitcnt vmcnt(6)
	s_barrier
	v_or_b32_e32 v112, s100, v77
	v_add_u32_e32 v113, v112, v78
	v_add_u32_e32 v112, v112, v79
	ds_read_b128 v[80:83], v113 offset:16384
	ds_read_b128 v[84:87], v113 offset:17408
	ds_read_b128 v[88:91], v113 offset:18432
	ds_read_b128 v[92:95], v113 offset:19456
	ds_read_b128 v[96:99], v112
	ds_read_b128 v[100:103], v112 offset:1024
	ds_read_b128 v[104:107], v112 offset:2048
	ds_read_b128 v[108:111], v112 offset:3072
	s_add_i32 s100, s100, 0x6000
	s_cmp_eq_u32 s100, 0x12000
	s_cselect_b32 s100, 0, s100
	s_cmp_ge_u32 s33, 0x100
	s_cbranch_scc1 .Lpp_B_1

; template <int MODE, bool SWAP, int MT>
; DI void gemm_tile(const int wv_, const Params& p, const u16* __restrict__ A, const u16* __restrict__ Bt, int brow, int bcol, char* smem, const float* gnext) {
;     ...
;   const int tid = tid_, wid = tid >> 6, lane = tid & 63, wr = wid >> 1, wc = wid & 1, fr = lane & 15, fq = lane >> 4;
;   f32x4 acc[MT][4];
; #pragma unroll
;   for (int m = 0; m < MT; ++m)
; #pragma unroll
;     for (int n = 0; n < 4; ++n) acc[m][n] = f32x4{0.f, 0.f, 0.f, 0.f};
;   const int ra = tid >> 2, cb = (tid & 3) * 8;
;   const u16* ga0 = A + (size_t)(brow + ra) * 1024 + cb;
;   const u16* ga1 = A + (size_t)(brow + 128 + ra) * 1024 + cb;
;   const u16* gb0 = Bt + (size_t)(bcol + ra) * 1024 + cb;
;   auto stage = [&](int t, int buf) {
;     char* sA = smem + buf * 24576; char* sB = sA + 16384;
;     if (MT >= 2 || tid < 256) __builtin_amdgcn_global_load_lds((const unsigned*)(ga0 + t * 32), (unsigned*)(sA + tid * 16), 16, 0, 0);
;     if (MT == 4) __builtin_amdgcn_global_load_lds((const unsigned*)(ga1 + t * 32), (unsigned*)(sA + 8192 + tid * 16), 16, 0, 0);
;     __builtin_amdgcn_global_load_lds((const unsigned*)(gb0 + t * 32), (unsigned*)(sB + tid * 16), 16, 0, 0);
;   };
;   stage(0, 0);
;   for (int t = 0; t < 32; ++t) {
;     asm volatile("s_waitcnt vmcnt(0)" ::: "memory");
;     __syncthreads();
;     if (t + 1 < 32) stage(t + 1, (t + 1) & 1);
;     const char* sA = smem + (t & 1) * 24576; const char* sB = sA + 16384;
;     bf16x8 Af[MT], Bf[4];
; #pragma unroll
;     for (int n = 0; n < 4; ++n) Bf[n] = *(const bf16x8*)(sB + (wc * 64 + n * 16 + fr) * 64 + fq * 16);
;     constexpr int MH = MT >= 2 ? MT / 2 : 1;
; #pragma unroll
;     for (int m = 0; m < MH; ++m) Af[m] = *(const bf16x8*)(sA + (wr * (16 * MT) + m * 16 + fr) * 64 + fq * 16);
.LBB0_88:
	s_and_b64 vcc, exec, s[0:1]
	s_cbranch_vccz .LBB0_83
	s_mov_b32 s1, 0
	v_readlane_b32 s20, v127, 0
	v_mbcnt_lo_u32_b32 v0, -1, s1
	v_mbcnt_hi_u32_b32 v0, -1, v0
	v_add_u32_e32 v12, s33, v0
	s_mov_b32 s1, s16
	v_ashrrev_i32_e32 v13, 2, v12
	v_add_u32_e32 v0, s18, v13
	s_mov_b32 s1, s17
	v_ashrrev_i32_e32 v1, 31, v0
	v_lshlrev_b64 v[4:5], 11, v[0:1]
	v_readlane_b32 s21, v127, 1
	v_lshlrev_b32_e32 v76, 4, v12
	v_lshrrev_b32_e32 v2, 8, v76
	v_sub_u32_e32 v2, 0, v2
	v_lshlrev_b32_e32 v2, 4, v2
	v_xor_b32_e32 v2, v2, v76
	v_and_b32_e32 v2, 48, v2
	v_lshl_add_u64 v[6:7], s[20:21], 0, v[4:5]
	v_add_u32_e32 v0, 0x80, v0
	v_readfirstlane_b32 s1, v76
	v_lshl_add_u64 v[6:7], v[6:7], 0, v[2:3]
	v_ashrrev_i32_e32 v1, 31, v0
	s_mov_b32 m0, s1
	v_lshlrev_b64 v[8:9], 11, v[0:1]
	global_load_lds_dwordx4 v[6:7], off
	v_add_u32_e32 v6, 0x2000, v76
	v_lshl_add_u64 v[0:1], s[20:21], 0, v[8:9]
	v_add_u32_e32 v10, s15, v13
	v_readfirstlane_b32 s1, v6
	v_lshl_add_u64 v[0:1], v[0:1], 0, v[2:3]
	v_ashrrev_i32_e32 v11, 31, v10
	s_mov_b32 m0, s1
	v_lshlrev_b64 v[10:11], 11, v[10:11]
	global_load_lds_dwordx4 v[0:1], off
	v_add_u32_e32 v0, 0x4000, v76
	v_lshl_add_u64 v[10:11], s[2:3], 0, v[10:11]
	v_readfirstlane_b32 s1, v0
	v_lshl_add_u64 v[10:11], v[10:11], 0, v[2:3]
	s_mov_b32 m0, s1
	v_and_b32_e32 v73, 15, v12
	global_load_lds_dwordx4 v[10:11], off
	v_readlane_b32 s20, v127, 22
	v_bfe_u32 v72, v12, 6, 1
	v_ashrrev_i32_e32 v74, 7, v12
	v_lshlrev_b32_e32 v0, 6, v73
	v_or_b32_e32 v4, v4, v2
	v_readlane_b32 s21, v127, 23
	v_lshl_or_b32 v78, v72, 12, v0
	v_lshl_or_b32 v79, v74, 12, v0
	v_lshl_add_u64 v[0:1], s[20:21], 0, v[4:5]
	v_add_u32_e32 v4, s12, v13
	v_subrev_u32_e32 v4, s19, v4
	v_ashrrev_i32_e32 v5, 31, v4
	v_lshlrev_b64 v[4:5], 11, v[4:5]
	v_or_b32_e32 v4, v4, v2
	v_bfe_u32 v75, v12, 4, 2
	v_or_b32_e32 v8, v8, v2
	v_lshl_add_u64 v[70:71], s[4:5], 0, v[4:5]
	v_mov_b32_e32 v4, 0
	s_mov_b32 s0, 0
	v_lshrrev_b32_e32 v77, 2, v73
	v_sub_u32_e32 v77, 0, v77
	v_xor_b32_e32 v77, v77, v75
	v_and_b32_e32 v77, 3, v77
	v_lshlrev_b32_e32 v77, 4, v77
	v_lshl_add_u64 v[68:69], s[20:21], 0, v[8:9]
	v_mov_b32_e32 v5, v4
	v_mov_b32_e32 v6, v4
	v_mov_b32_e32 v7, v4
	v_mov_b32_e32 v8, v4
	v_mov_b32_e32 v9, v4
	v_mov_b32_e32 v10, v4
	v_mov_b32_e32 v11, v4
	v_mov_b32_e32 v12, v4
	v_mov_b32_e32 v13, v4
	v_mov_b32_e32 v14, v4
	v_mov_b32_e32 v15, v4
	v_mov_b32_e32 v16, v4
	v_mov_b32_e32 v17, v4
	v_mov_b32_e32 v18, v4
	v_mov_b32_e32 v19, v4
	v_mov_b32_e32 v20, v4
	v_mov_b32_e32 v21, v4
	v_mov_b32_e32 v22, v4
	v_mov_b32_e32 v23, v4
	v_mov_b32_e32 v24, v4
	v_mov_b32_e32 v25, v4
	v_mov_b32_e32 v26, v4
	v_mov_b32_e32 v27, v4
	v_mov_b32_e32 v28, v4
	v_mov_b32_e32 v29, v4
	v_mov_b32_e32 v30, v4
	v_mov_b32_e32 v31, v4
	v_mov_b32_e32 v32, v4
	v_mov_b32_e32 v33, v4
	v_mov_b32_e32 v34, v4
	v_mov_b32_e32 v35, v4
	v_mov_b32_e32 v36, v4
	v_mov_b32_e32 v37, v4
	v_mov_b32_e32 v38, v4
	v_mov_b32_e32 v39, v4
	v_mov_b32_e32 v40, v4
	v_mov_b32_e32 v41, v4
	v_mov_b32_e32 v42, v4
	v_mov_b32_e32 v43, v4
	v_mov_b32_e32 v44, v4
	v_mov_b32_e32 v45, v4
	v_mov_b32_e32 v46, v4
	v_mov_b32_e32 v47, v4
	v_mov_b32_e32 v48, v4
	v_mov_b32_e32 v49, v4
	v_mov_b32_e32 v50, v4
	v_mov_b32_e32 v51, v4
	v_mov_b32_e32 v52, v4
	v_mov_b32_e32 v53, v4
	v_mov_b32_e32 v54, v4
	v_mov_b32_e32 v55, v4
	v_mov_b32_e32 v56, v4
	v_mov_b32_e32 v57, v4
	v_mov_b32_e32 v58, v4
	v_mov_b32_e32 v59, v4
	v_mov_b32_e32 v60, v4
	v_mov_b32_e32 v61, v4
	v_mov_b32_e32 v62, v4
	v_mov_b32_e32 v63, v4
	v_mov_b32_e32 v64, v4
	v_mov_b32_e32 v65, v4
	v_mov_b32_e32 v66, v4
	v_mov_b32_e32 v67, v4
	v_readlane_b32 s22, v127, 2
	v_readlane_b32 s23, v127, 3
	v_readfirstlane_b32 s98, v76
	s_movk_i32 s99, 0x6000
	s_add_i32 s101, s98, s99
	s_mov_b32 m0, s101
	s_add_i32 s101, s101, 0x2000
	global_load_lds_dwordx4 v[0:1], off
	s_mov_b32 m0, s101
	s_add_i32 s101, s101, 0x2000
	global_load_lds_dwordx4 v[68:69], off
	s_mov_b32 m0, s101
	s_add_i32 s99, s99, 0x6000
	global_load_lds_dwordx4 v[70:71], off
	s_cmp_eq_u32 s99, 0x12000
	s_cselect_b32 s99, 0, s99
	v_lshl_add_u64 v[0:1], v[0:1], 0, 64
	v_lshl_add_u64 v[68:69], v[68:69], 0, 64
	v_lshl_add_u64 v[70:71], v[70:71], 0, 64
	s_add_i32 s101, s98, s99
	s_mov_b32 m0, s101
	s_add_i32 s101, s101, 0x2000
	global_load_lds_dwordx4 v[0:1], off
	s_mov_b32 m0, s101
	s_add_i32 s101, s101, 0x2000
	global_load_lds_dwordx4 v[68:69], off
	s_mov_b32 m0, s101
	s_add_i32 s99, s99, 0x6000
	global_load_lds_dwordx4 v[70:71], off
	s_cmp_eq_u32 s99, 0x12000
	s_cselect_b32 s99, 0, s99
	v_lshl_add_u64 v[0:1], v[0:1], 0, 64
	v_lshl_add_u64 v[68:69], v[68:69], 0, 64
	v_lshl_add_u64 v[70:71], v[70:71], 0, 64
	s_mov_b32 s100, 0
	s_waitcnt vmcnt(6)
	s_barrier
	v_or_b32_e32 v112, s100, v77
	v_add_u32_e32 v113, v112, v78
	v_add_u32_e32 v112, v112, v79
	ds_read_b128 v[80:83], v113 offset:16384
	ds_read_b128 v[84:87], v113 offset:17408
	ds_read_b128 v[88:91], v113 offset:18432
	ds_read_b128 v[92:95], v113 offset:19456
	ds_read_b128 v[96:99], v112
	ds_read_b128 v[100:103], v112 offset:1024
	ds_read_b128 v[104:107], v112 offset:2048
	ds_read_b128 v[108:111], v112 offset:3072
	s_add_i32 s100, s100, 0x6000
	s_cmp_eq_u32 s100, 0x12000
	s_cselect_b32 s100, 0, s100
	s_cmp_ge_u32 s33, 0x100
	s_cbranch_scc1 .Lpp_B_2

; template <int MODE, bool SWAP, int MT>
; DI void gemm_tile(const int wv_, const Params& p, const u16* __restrict__ A, const u16* __restrict__ Bt, int brow, int bcol, char* smem, const float* gnext) {
;     ...
;   const int tid = tid_, wid = tid >> 6, lane = tid & 63, wr = wid >> 1, wc = wid & 1, fr = lane & 15, fq = lane >> 4;
;   f32x4 acc[MT][4];
; #pragma unroll
;   for (int m = 0; m < MT; ++m)
; #pragma unroll
;     for (int n = 0; n < 4; ++n) acc[m][n] = f32x4{0.f, 0.f, 0.f, 0.f};
;   const int ra = tid >> 2, cb = (tid & 3) * 8;
;   const u16* ga0 = A + (size_t)(brow + ra) * 1024 + cb;
;   const u16* ga1 = A + (size_t)(brow + 128 + ra) * 1024 + cb;
;   const u16* gb0 = Bt + (size_t)(bcol + ra) * 1024 + cb;
;   auto stage = [&](int t, int buf) {
;     char* sA = smem + buf * 24576; char* sB = sA + 16384;
;     if (MT >= 2 || tid < 256) __builtin_amdgcn_global_load_lds((const unsigned*)(ga0 + t * 32), (unsigned*)(sA + tid * 16), 16, 0, 0);
;     if (MT == 4) __builtin_amdgcn_global_load_lds((const unsigned*)(ga1 + t * 32), (unsigned*)(sA + 8192 + tid * 16), 16, 0, 0);
;     __builtin_amdgcn_global_load_lds((const unsigned*)(gb0 + t * 32), (unsigned*)(sB + tid * 16), 16, 0, 0);
;   };
;   stage(0, 0);
;   for (int t = 0; t < 32; ++t) {
;     asm volatile("s_waitcnt vmcnt(0)" ::: "memory");
;     __syncthreads();
;     if (t + 1 < 32) stage(t + 1, (t + 1) & 1);
;     const char* sA = smem + (t & 1) * 24576; const char* sB = sA + 16384;
;     bf16x8 Af[MT], Bf[4];
; #pragma unroll
;     for (int n = 0; n < 4; ++n) Bf[n] = *(const bf16x8*)(sB + (wc * 64 + n * 16 + fr) * 64 + fq * 16);
;     constexpr int MH = MT >= 2 ? MT / 2 : 1;
; #pragma unroll
;     for (int m = 0; m < MH; ++m) Af[m] = *(const bf16x8*)(sA + (wr * (16 * MT) + m * 16 + fr) * 64 + fq * 16);
; template <int MODE>
; DI void phase_gemm(const int wv_, const Params& p, const u16* A, const u16* Bt, int NT, char* smem, const float* gnext) {
;     ...
;     int tm = tile / NT, tn = tile - tm * NT;
;     if (MODE == 1 && tn >= 20 && tn < 24) gemm_tile<1, false, 4>(wv_, p, A, Bt, tm * 256, tn * 128, smem, gnext);
;     else gemm_tile<MODE, true, 4>(wv_, p, A, Bt, tm * 256, tn * 128, smem, gnext);
.LBB0_372:
	s_mul_hi_i32 s0, s22, 0x3e0f83e1
	s_mov_b32 s7, 0
	s_lshr_b32 s1, s0, 31
	s_ashr_i32 s0, s0, 3
	s_add_i32 s6, s0, s1
	v_mbcnt_lo_u32_b32 v0, -1, s7
	v_mbcnt_hi_u32_b32 v0, -1, v0
	s_mul_i32 s0, s6, 0xffffffdf
	v_add_u32_e32 v2, s33, v0
	s_add_i32 s1, s0, s22
	s_lshl_b32 s0, s6, 8
	s_mov_b32 s7, s16
	v_ashrrev_i32_e32 v12, 2, v2
	v_add_u32_e32 v0, s0, v12
	s_mov_b32 s7, s17
	v_ashrrev_i32_e32 v1, 31, v0
	v_readlane_b32 s8, v127, 0
	v_lshlrev_b64 v[4:5], 11, v[0:1]
	v_readlane_b32 s9, v127, 1
	v_lshlrev_b32_e32 v76, 4, v2
	v_bfe_u32 v72, v2, 6, 1
	v_ashrrev_i32_e32 v74, 7, v2
	v_and_b32_e32 v75, 15, v2
	v_bfe_u32 v73, v2, 4, 2
	v_lshl_add_u64 v[6:7], s[8:9], 0, v[4:5]
	v_lshrrev_b32_e32 v2, 8, v76
	v_sub_u32_e32 v2, 0, v2
	v_lshlrev_b32_e32 v2, 4, v2
	v_xor_b32_e32 v2, v2, v76
	v_and_b32_e32 v2, 48, v2
	v_add_u32_e32 v0, 0x80, v0
	v_readfirstlane_b32 s7, v76
	v_lshl_add_u64 v[6:7], v[6:7], 0, v[2:3]
	v_ashrrev_i32_e32 v1, 31, v0
	s_mov_b32 m0, s7
	s_lshl_b32 s23, s1, 7
	v_lshlrev_b64 v[8:9], 11, v[0:1]
	global_load_lds_dwordx4 v[6:7], off
	v_add_u32_e32 v6, 0x2000, v76
	v_lshl_add_u64 v[0:1], s[8:9], 0, v[8:9]
	v_add_u32_e32 v10, s23, v12
	v_readfirstlane_b32 s7, v6
	v_lshl_add_u64 v[0:1], v[0:1], 0, v[2:3]
	v_ashrrev_i32_e32 v11, 31, v10
	s_mov_b32 m0, s7
	v_lshlrev_b64 v[10:11], 11, v[10:11]
	global_load_lds_dwordx4 v[0:1], off
	v_add_u32_e32 v0, 0x4000, v76
	v_lshl_add_u64 v[10:11], s[2:3], 0, v[10:11]
	v_readfirstlane_b32 s7, v0
	v_lshl_add_u64 v[10:11], v[10:11], 0, v[2:3]
	s_mov_b32 m0, s7
	v_readlane_b32 s8, v127, 22
	global_load_lds_dwordx4 v[10:11], off
	v_lshlrev_b32_e32 v0, 6, v75
	v_or_b32_e32 v4, v4, v2
	v_readlane_b32 s9, v127, 23
	v_lshl_or_b32 v78, v72, 12, v0
	v_lshl_or_b32 v79, v74, 12, v0
	v_lshl_add_u64 v[0:1], s[8:9], 0, v[4:5]
	v_add_u32_e32 v4, s20, v12
	s_mulk_i32 s6, 0x1080
	v_subrev_u32_e32 v4, s6, v4
	v_ashrrev_i32_e32 v5, 31, v4
	v_lshlrev_b64 v[4:5], 11, v[4:5]
	v_or_b32_e32 v4, v4, v2
	v_or_b32_e32 v8, v8, v2
	v_lshl_add_u64 v[70:71], s[4:5], 0, v[4:5]
	v_mov_b32_e32 v4, 0
	s_mov_b32 s1, 0
	v_lshrrev_b32_e32 v77, 2, v75
	v_sub_u32_e32 v77, 0, v77
	v_xor_b32_e32 v77, v77, v73
	v_and_b32_e32 v77, 3, v77
	v_lshlrev_b32_e32 v77, 4, v77
	v_lshl_add_u64 v[68:69], s[8:9], 0, v[8:9]
	v_mov_b32_e32 v5, v4
	v_mov_b32_e32 v6, v4
	v_mov_b32_e32 v7, v4
	v_mov_b32_e32 v8, v4
	v_mov_b32_e32 v9, v4
	v_mov_b32_e32 v10, v4
	v_mov_b32_e32 v11, v4
	v_mov_b32_e32 v12, v4
	v_mov_b32_e32 v13, v4
	v_mov_b32_e32 v14, v4
	v_mov_b32_e32 v15, v4
	v_mov_b32_e32 v16, v4
	v_mov_b32_e32 v17, v4
	v_mov_b32_e32 v18, v4
	v_mov_b32_e32 v19, v4
	v_mov_b32_e32 v20, v4
	v_mov_b32_e32 v21, v4
	v_mov_b32_e32 v22, v4
	v_mov_b32_e32 v23, v4
	v_mov_b32_e32 v24, v4
	v_mov_b32_e32 v25, v4
	v_mov_b32_e32 v26, v4
	v_mov_b32_e32 v27, v4
	v_mov_b32_e32 v28, v4
	v_mov_b32_e32 v29, v4
	v_mov_b32_e32 v30, v4
	v_mov_b32_e32 v31, v4
	v_mov_b32_e32 v32, v4
	v_mov_b32_e32 v33, v4
	v_mov_b32_e32 v34, v4
	v_mov_b32_e32 v35, v4
	v_mov_b32_e32 v44, v4
	v_mov_b32_e32 v45, v4
	v_mov_b32_e32 v46, v4
	v_mov_b32_e32 v47, v4
	v_mov_b32_e32 v36, v4
	v_mov_b32_e32 v37, v4
	v_mov_b32_e32 v38, v4
	v_mov_b32_e32 v39, v4
	v_mov_b32_e32 v40, v4
	v_mov_b32_e32 v41, v4
	v_mov_b32_e32 v42, v4
	v_mov_b32_e32 v43, v4
	v_mov_b32_e32 v48, v4
	v_mov_b32_e32 v49, v4
	v_mov_b32_e32 v50, v4
	v_mov_b32_e32 v51, v4
	v_mov_b32_e32 v52, v4
	v_mov_b32_e32 v53, v4
	v_mov_b32_e32 v54, v4
	v_mov_b32_e32 v55, v4
	v_mov_b32_e32 v56, v4
	v_mov_b32_e32 v57, v4
	v_mov_b32_e32 v58, v4
	v_mov_b32_e32 v59, v4
	v_mov_b32_e32 v60, v4
	v_mov_b32_e32 v61, v4
	v_mov_b32_e32 v62, v4
	v_mov_b32_e32 v63, v4
	v_mov_b32_e32 v64, v4
	v_mov_b32_e32 v65, v4
	v_mov_b32_e32 v66, v4
	v_mov_b32_e32 v67, v4
	v_readlane_b32 s10, v127, 2
	v_readlane_b32 s11, v127, 3
	v_readfirstlane_b32 s98, v76
	s_movk_i32 s99, 0x6000
	s_add_i32 s101, s98, s99
	s_mov_b32 m0, s101
	s_add_i32 s101, s101, 0x2000
	global_load_lds_dwordx4 v[0:1], off
	s_mov_b32 m0, s101
	s_add_i32 s101, s101, 0x2000
	global_load_lds_dwordx4 v[68:69], off
	s_mov_b32 m0, s101
	s_add_i32 s99, s99, 0x6000
	global_load_lds_dwordx4 v[70:71], off
	s_cmp_eq_u32 s99, 0x12000
	s_cselect_b32 s99, 0, s99
	v_lshl_add_u64 v[0:1], v[0:1], 0, 64
	v_lshl_add_u64 v[68:69], v[68:69], 0, 64
	v_lshl_add_u64 v[70:71], v[70:71], 0, 64
	s_add_i32 s101, s98, s99
	s_mov_b32 m0, s101
	s_add_i32 s101, s101, 0x2000
	global_load_lds_dwordx4 v[0:1], off
	s_mov_b32 m0, s101
	s_add_i32 s101, s101, 0x2000
	global_load_lds_dwordx4 v[68:69], off
	s_mov_b32 m0, s101
	s_add_i32 s99, s99, 0x6000
	global_load_lds_dwordx4 v[70:71], off
	s_cmp_eq_u32 s99, 0x12000
	s_cselect_b32 s99, 0, s99
	v_lshl_add_u64 v[0:1], v[0:1], 0, 64
	v_lshl_add_u64 v[68:69], v[68:69], 0, 64
	v_lshl_add_u64 v[70:71], v[70:71], 0, 64
	s_mov_b32 s100, 0
	s_waitcnt vmcnt(6)
	s_barrier
	v_or_b32_e32 v112, s100, v77
	v_add_u32_e32 v113, v112, v78
	v_add_u32_e32 v112, v112, v79
	ds_read_b128 v[80:83], v113 offset:16384
	ds_read_b128 v[84:87], v113 offset:17408
	ds_read_b128 v[88:91], v113 offset:18432
	ds_read_b128 v[92:95], v113 offset:19456
	ds_read_b128 v[96:99], v112
	ds_read_b128 v[100:103], v112 offset:1024
	ds_read_b128 v[104:107], v112 offset:2048
	ds_read_b128 v[108:111], v112 offset:3072
	s_add_i32 s100, s100, 0x6000
	s_cmp_eq_u32 s100, 0x12000
	s_cselect_b32 s100, 0, s100
	s_cmp_ge_u32 s33, 0x100
	s_cbranch_scc1 .Lpp_B_3

; template <int MODE, bool SWAP, int MT>
; DI void gemm_tile(const int wv_, const Params& p, const u16* __restrict__ A, const u16* __restrict__ Bt, int brow, int bcol, char* smem, const float* gnext) {
;     ...
;   const int tid = tid_, wid = tid >> 6, lane = tid & 63, wr = wid >> 1, wc = wid & 1, fr = lane & 15, fq = lane >> 4;
;   f32x4 acc[MT][4];
; #pragma unroll
;   for (int m = 0; m < MT; ++m)
; #pragma unroll
;     for (int n = 0; n < 4; ++n) acc[m][n] = f32x4{0.f, 0.f, 0.f, 0.f};
;   const int ra = tid >> 2, cb = (tid & 3) * 8;
;   const u16* ga0 = A + (size_t)(brow + ra) * 1024 + cb;
;   const u16* ga1 = A + (size_t)(brow + 128 + ra) * 1024 + cb;
;   const u16* gb0 = Bt + (size_t)(bcol + ra) * 1024 + cb;
;   auto stage = [&](int t, int buf) {
;     char* sA = smem + buf * 24576; char* sB = sA + 16384;
;     if (MT >= 2 || tid < 256) __builtin_amdgcn_global_load_lds((const unsigned*)(ga0 + t * 32), (unsigned*)(sA + tid * 16), 16, 0, 0);
;     if (MT == 4) __builtin_amdgcn_global_load_lds((const unsigned*)(ga1 + t * 32), (unsigned*)(sA + 8192 + tid * 16), 16, 0, 0);
;     __builtin_amdgcn_global_load_lds((const unsigned*)(gb0 + t * 32), (unsigned*)(sB + tid * 16), 16, 0, 0);
;   };
;   stage(0, 0);
;   for (int t = 0; t < 32; ++t) {
;     asm volatile("s_waitcnt vmcnt(0)" ::: "memory");
;     __syncthreads();
;     if (t + 1 < 32) stage(t + 1, (t + 1) & 1);
;     const char* sA = smem + (t & 1) * 24576; const char* sB = sA + 16384;
;     bf16x8 Af[MT], Bf[4];
; #pragma unroll
;     for (int n = 0; n < 4; ++n) Bf[n] = *(const bf16x8*)(sB + (wc * 64 + n * 16 + fr) * 64 + fq * 16);
;     constexpr int MH = MT >= 2 ? MT / 2 : 1;
; #pragma unroll
;     for (int m = 0; m < MH; ++m) Af[m] = *(const bf16x8*)(sA + (wr * (16 * MT) + m * 16 + fr) * 64 + fq * 16);
; template <int MODE>
; DI void phase_gemm(const int wv_, const Params& p, const u16* A, const u16* Bt, int NT, char* smem, const float* gnext) {
;     ...
;     int tm = tile / NT, tn = tile - tm * NT;
;     if (MODE == 1 && tn >= 20 && tn < 24) gemm_tile<1, false, 4>(wv_, p, A, Bt, tm * 256, tn * 128, smem, gnext);
;     else gemm_tile<MODE, true, 4>(wv_, p, A, Bt, tm * 256, tn * 128, smem, gnext);
.LBB0_828:
	s_ashr_i32 s0, s28, 31
	s_mov_b32 s3, 0
	s_lshr_b32 s0, s0, 29
	s_add_i32 s0, s28, s0
	v_mbcnt_lo_u32_b32 v0, -1, s3
	v_mbcnt_hi_u32_b32 v0, -1, v0
	s_ashr_i32 s1, s0, 3
	v_add_u32_e32 v77, s33, v0
	s_lshl_b32 s0, s1, 8
	s_mov_b32 s3, s16
	v_ashrrev_i32_e32 v12, 2, v77
	v_add_u32_e32 v0, s0, v12
	s_mov_b32 s3, s17
	s_waitcnt lgkmcnt(0)
	v_ashrrev_i32_e32 v1, 31, v0
	v_lshlrev_b64 v[4:5], 11, v[0:1]
	v_lshlrev_b32_e32 v74, 4, v77
	v_lshl_add_u64 v[6:7], s[50:51], 0, v[4:5]
	v_lshrrev_b32_e32 v2, 8, v74
	v_sub_u32_e32 v2, 0, v2
	v_lshlrev_b32_e32 v2, 4, v2
	v_xor_b32_e32 v2, v2, v74
	v_and_b32_e32 v2, 48, v2
	v_add_u32_e32 v0, 0x80, v0
	v_readfirstlane_b32 s3, v74
	s_lshl_b32 s2, s1, 10
	s_lshl_b32 s1, s28, 7
	v_lshl_add_u64 v[6:7], v[6:7], 0, v[2:3]
	v_ashrrev_i32_e32 v1, 31, v0
	s_mov_b32 m0, s3
	s_sub_i32 s12, s1, s2
	v_lshlrev_b64 v[8:9], 11, v[0:1]
	global_load_lds_dwordx4 v[6:7], off
	v_add_u32_e32 v6, 0x2000, v74
	v_lshl_add_u64 v[0:1], s[50:51], 0, v[8:9]
	v_add_u32_e32 v10, s12, v12
	v_readfirstlane_b32 s3, v6
	v_lshl_add_u64 v[0:1], v[0:1], 0, v[2:3]
	v_ashrrev_i32_e32 v11, 31, v10
	s_mov_b32 m0, s3
	v_lshlrev_b64 v[10:11], 11, v[10:11]
	global_load_lds_dwordx4 v[0:1], off
	v_add_u32_e32 v0, 0x4000, v74
	v_lshl_add_u64 v[10:11], s[6:7], 0, v[10:11]
	v_readfirstlane_b32 s3, v0
	v_lshl_add_u64 v[10:11], v[10:11], 0, v[2:3]
	s_mov_b32 m0, s3
	v_and_b32_e32 v73, 15, v77
	global_load_lds_dwordx4 v[10:11], off
	v_readlane_b32 s4, v127, 28
	v_bfe_u32 v76, v77, 6, 1
	v_ashrrev_i32_e32 v72, 7, v77
	v_lshlrev_b32_e32 v0, 6, v73
	v_or_b32_e32 v4, v4, v2
	v_readlane_b32 s5, v127, 29
	v_lshl_or_b32 v78, v76, 12, v0
	v_lshl_or_b32 v79, v72, 12, v0
	v_lshl_add_u64 v[0:1], s[4:5], 0, v[4:5]
	v_add_u32_e32 v4, s23, v12
	v_subrev_u32_e32 v4, s2, v4
	v_ashrrev_i32_e32 v5, 31, v4
	v_lshlrev_b64 v[4:5], 11, v[4:5]
	v_readlane_b32 s2, v127, 30
	v_or_b32_e32 v4, v4, v2
	v_readlane_b32 s3, v127, 31
	v_or_b32_e32 v8, v8, v2
	s_mov_b32 s1, 0
	v_lshl_add_u64 v[70:71], s[2:3], 0, v[4:5]
	v_mov_b32_e32 v4, 0
	v_lshrrev_b32_e32 v75, 2, v73
	v_sub_u32_e32 v75, 0, v75
	v_lshlrev_b32_e32 v75, 4, v75
	v_xor_b32_e32 v75, v75, v77
	v_and_b32_e32 v75, 48, v75
	v_lshl_add_u64 v[68:69], s[4:5], 0, v[8:9]
	v_mov_b32_e32 v5, v4
	v_mov_b32_e32 v6, v4
	v_mov_b32_e32 v7, v4
	v_mov_b32_e32 v8, v4
	v_mov_b32_e32 v9, v4
	v_mov_b32_e32 v10, v4
	v_mov_b32_e32 v11, v4
	v_mov_b32_e32 v12, v4
	v_mov_b32_e32 v13, v4
	v_mov_b32_e32 v14, v4
	v_mov_b32_e32 v15, v4
	v_mov_b32_e32 v16, v4
	v_mov_b32_e32 v17, v4
	v_mov_b32_e32 v18, v4
	v_mov_b32_e32 v19, v4
	v_mov_b32_e32 v20, v4
	v_mov_b32_e32 v21, v4
	v_mov_b32_e32 v22, v4
	v_mov_b32_e32 v23, v4
	v_mov_b32_e32 v24, v4
	v_mov_b32_e32 v25, v4
	v_mov_b32_e32 v26, v4
	v_mov_b32_e32 v27, v4
	v_mov_b32_e32 v28, v4
	v_mov_b32_e32 v29, v4
	v_mov_b32_e32 v30, v4
	v_mov_b32_e32 v31, v4
	v_mov_b32_e32 v32, v4
	v_mov_b32_e32 v33, v4
	v_mov_b32_e32 v34, v4
	v_mov_b32_e32 v35, v4
	v_mov_b32_e32 v36, v4
	v_mov_b32_e32 v37, v4
	v_mov_b32_e32 v38, v4
	v_mov_b32_e32 v39, v4
	v_mov_b32_e32 v40, v4
	v_mov_b32_e32 v41, v4
	v_mov_b32_e32 v42, v4
	v_mov_b32_e32 v43, v4
	v_mov_b32_e32 v44, v4
	v_mov_b32_e32 v45, v4
	v_mov_b32_e32 v46, v4
	v_mov_b32_e32 v47, v4
	v_mov_b32_e32 v48, v4
	v_mov_b32_e32 v49, v4
	v_mov_b32_e32 v50, v4
	v_mov_b32_e32 v51, v4
	v_mov_b32_e32 v52, v4
	v_mov_b32_e32 v53, v4
	v_mov_b32_e32 v54, v4
	v_mov_b32_e32 v55, v4
	v_mov_b32_e32 v56, v4
	v_mov_b32_e32 v57, v4
	v_mov_b32_e32 v58, v4
	v_mov_b32_e32 v59, v4
	v_mov_b32_e32 v60, v4
	v_mov_b32_e32 v61, v4
	v_mov_b32_e32 v62, v4
	v_mov_b32_e32 v63, v4
	v_mov_b32_e32 v64, v4
	v_mov_b32_e32 v65, v4
	v_mov_b32_e32 v66, v4
	v_mov_b32_e32 v67, v4
	v_readfirstlane_b32 s98, v74
	s_movk_i32 s99, 0x6000
	s_add_i32 s101, s98, s99
	s_mov_b32 m0, s101
	s_add_i32 s101, s101, 0x2000
	global_load_lds_dwordx4 v[0:1], off
	s_mov_b32 m0, s101
	s_add_i32 s101, s101, 0x2000
	global_load_lds_dwordx4 v[68:69], off
	s_mov_b32 m0, s101
	s_add_i32 s99, s99, 0x6000
	global_load_lds_dwordx4 v[70:71], off
	s_cmp_eq_u32 s99, 0x12000
	s_cselect_b32 s99, 0, s99
	v_lshl_add_u64 v[0:1], v[0:1], 0, 64
	v_lshl_add_u64 v[68:69], v[68:69], 0, 64
	v_lshl_add_u64 v[70:71], v[70:71], 0, 64
	s_add_i32 s101, s98, s99
	s_mov_b32 m0, s101
	s_add_i32 s101, s101, 0x2000
	global_load_lds_dwordx4 v[0:1], off
	s_mov_b32 m0, s101
	s_add_i32 s101, s101, 0x2000
	global_load_lds_dwordx4 v[68:69], off
	s_mov_b32 m0, s101
	s_add_i32 s99, s99, 0x6000
	global_load_lds_dwordx4 v[70:71], off
	s_cmp_eq_u32 s99, 0x12000
	s_cselect_b32 s99, 0, s99
	v_lshl_add_u64 v[0:1], v[0:1], 0, 64
	v_lshl_add_u64 v[68:69], v[68:69], 0, 64
	v_lshl_add_u64 v[70:71], v[70:71], 0, 64
	s_mov_b32 s100, 0
	s_waitcnt vmcnt(6)
	s_barrier
	v_or_b32_e32 v112, s100, v75
	v_add_u32_e32 v113, v112, v78
	v_add_u32_e32 v112, v112, v79
	ds_read_b128 v[80:83], v113 offset:16384
	ds_read_b128 v[84:87], v113 offset:17408
	ds_read_b128 v[88:91], v113 offset:18432
	ds_read_b128 v[92:95], v113 offset:19456
	ds_read_b128 v[96:99], v112
	ds_read_b128 v[100:103], v112 offset:1024
	ds_read_b128 v[104:107], v112 offset:2048
	ds_read_b128 v[108:111], v112 offset:3072
	s_add_i32 s100, s100, 0x6000
	s_cmp_eq_u32 s100, 0x12000
	s_cselect_b32 s100, 0, s100
	s_cmp_ge_u32 s33, 0x100
	s_cbranch_scc1 .Lpp_B_4
